# P4: second sub-block runs its S5 outputs before its SSD units (roles staggered between the two sub-blocks)
# baseline (speedup 1.0000x reference)
; #define LAS __attribute__((address_space(3)))
; __device__ __forceinline__ void ssd_passC_unit(const Args& a, LAS unsigned char* lds, int unit, int tid, int w4, int lane, LAS unsigned* bcnt, unsigned& btarget) {
;     const int ubc = unit >> 1, g = unit & 1;
;     const SeqInfo si = ssd_unit(ubc);
;     sub_barrier(bcnt, btarget, lane);
;     ssd_cs(a, lds, si, g, lane, 1, nullptr);
;     ssd_stage(a, lds, si, g, ubc & 127, tid, 1);
;     sub_barrier(bcnt, btarget, lane);
;     const int h4 = w4, r = lane & 31, hf = lane >> 5, h = g * 4 + h4;
;     const LAS bf16_t* XT = (const LAS bf16_t*)(lds + L_XT) + h4 * 64 * XT_LD; const LAS bf16_t* Bn = (const LAS bf16_t*)(lds + L_BT); const LAS bf16_t* Cn = (const LAS bf16_t*)(lds + L_CN);
;     const LAS float* cs = (const LAS float*)(lds + L_CS) + h4 * 64; const LAS float* dtl = cs + 256; const LAS float* ecs = cs + 512; LAS float* red = (LAS float*)(lds + L_CS) + 768;
; __global__ void __launch_bounds__(512, 2) fwd_kernel(Args a) {
;     ...
;             const int sb = wave >> 2, sid = tid & 255, w4 = wave & 3;
;             LAS unsigned char* sl = lds + sb * SUB_LDS; LAS unsigned* bcnt = (LAS unsigned*)(sl + L_SSD_END);
;             if (sid == 0) *bcnt = 0u;
;             __syncthreads();
;             unsigned btarget = 0u;
;             const bool spread = (G == 256);
;             const int ulim = spread ? NBATCH * NCHUNK * 2 : NUNITS_BC * 2, u0 = bx * 2 + sb;
;             const int nk = u0 < ulim ? (ulim - u0 + 2 * G - 1) / (2 * G) : 0;
;             const int sj = (spread && sb == 0 && (bx & 15) == 8) ? (bx >> 4) : -1;
;             if (sb) __builtin_amdgcn_s_sleep(100);
;             for (int k = 0; k < nk + (sj >= 0 ? 1 : 0); ++k) ssd_passC_unit(a, sl, k < nk ? u0 + k * 2 * G : NBATCH * NCHUNK * 2 + sj, sid, w4, lane, bcnt, btarget);
.LBB0_616:
	s_and_b32 s4, s96, 15
	s_cmp_eq_u32 s4, 8
	s_cselect_b64 s[4:5], -1, 0
	s_and_b64 s[2:3], s[4:5], s[2:3]
	s_and_b64 s[0:1], s[2:3], s[0:1]
	s_ashr_i32 s2, s96, 4
	s_and_b64 s[0:1], s[0:1], exec
	s_cselect_b32 s75, s2, -1
	s_not_b32 s0, s75
	s_lshr_b32 s0, s0, 31
	s_add_i32 s74, s69, s0
	v_readlane_b32 s0, v254, 1
	s_cmpk_lt_u32 s0, 0x100
	s_cbranch_scc1 .Lp4_normal
	s_mov_b32 s98, s70
	s_mov_b32 s99, s71
	s_mov_b32 s100, s72
	s_mov_b32 s101, s73
	s_branch .Lp4_s5_entry
.Lp4_normal:
	s_cmp_lt_i32 s74, 1
	v_cmp_gt_u32_e64 s[2:3], 32, v176
	s_cbranch_scc1 .LBB0_853
.Lp4_ssd_setup:
	v_readlane_b32 s0, v254, 1
	s_bfe_u32 s18, s0, 0x20006
	v_readlane_b32 s0, v254, 41
	v_readlane_b32 s1, v254, 42
	s_lshl_b32 s0, s0, 1
	v_lshlrev_b32_e32 v0, 2, v176
	v_writelane_b32 v255, s0, 1
	s_add_i32 s93, s16, 0x11c00
	s_add_i32 s0, s16, 0x12000
	s_add_i32 s1, s16, 0x12400
	v_or_b32_e32 v1, 0x100, v0
	v_add_u32_e32 v252, s93, v0
	v_add_u32_e32 v253, s0, v0
	v_add_u32_e32 v208, s1, v0
	v_add_u32_e32 v211, s93, v1
	v_add_u32_e32 v200, s0, v1
	v_add_u32_e32 v201, s1, v1
	v_or_b32_e32 v1, 0x200, v0
	v_or_b32_e32 v0, 0x300, v0
	v_add_u32_e32 v203, s0, v1
	v_add_u32_e32 v204, s1, v1
	v_add_u32_e32 v206, s0, v0
	v_add_u32_e32 v207, s1, v0
	v_cmp_lt_u32_e64 s[0:1], 47, v176
	s_addk_i32 s75, 0x800
	v_add_u32_e32 v205, s93, v0
	v_writelane_b32 v254, s0, 63
	v_mov_b32_e32 v0, s16
	s_add_u32 s34, s88, 0x300000
	v_writelane_b32 v255, s1, 0
	s_movk_i32 s0, 0x480
	v_add_u32_e32 v202, s93, v1
	v_mad_u32_u24 v210, v176, s0, v0
	v_lshrrev_b32_e32 v1, 5, v176
	s_mul_i32 s0, s18, 0x2400
	s_addc_u32 s35, s89, 0
	v_and_b32_e32 v2, 7, v177
	s_add_i32 s0, s16, s0
	s_lshl_b32 s20, s18, 8
	s_add_i32 s94, s16, 0x12800
	v_lshlrev_b32_e32 v108, 3, v1
	s_add_i32 s93, s93, s20
	v_add_u32_e32 v4, s0, v108
	v_lshl_add_u32 v6, v2, 1, s0
	s_add_i32 s95, s94, s20
	s_lshl_b32 s0, s18, 7
	s_add_u32 s0, s88, s0
	s_addc_u32 s1, s89, 0
	v_lshlrev_b32_e32 v3, 4, v1
	s_add_u32 s96, s88, 0x1aa00000
	v_and_b32_e32 v212, 31, v177
	v_mov_b32_e32 v109, 0
	v_add_u32_e32 v213, s16, v3
	v_add_u32_e32 v214, s93, v3
	s_movk_i32 s21, 0x90
	v_lshlrev_b32_e32 v3, 1, v177
	v_or_b32_e32 v5, 32, v176
	s_addc_u32 s97, s89, 0
	v_lshl_add_u32 v209, v176, 4, s16
	v_mad_u32_u24 v222, v212, s21, v4
	v_and_b32_e32 v223, 48, v3
	v_bitop3_b32 v224, v3, 16, 48 bitop3:0x6c
	v_mad_u32_u24 v225, v5, s21, v4
	v_bitop3_b32 v226, v3, 32, 48 bitop3:0x6c
	v_bitop3_b32 v227, v3, 48, v3 bitop3:0xc
	v_mul_u32_u24_e32 v3, 0x110, v5
	v_lshl_add_u64 v[4:5], s[0:1], 0, v[108:109]
	s_mov_b64 s[16:17], 0xa800000
	s_add_u32 s80, s80, s20
	v_lshlrev_b32_e32 v106, 2, v1
	v_lshlrev_b32_e32 v0, 7, v212
	v_lshl_add_u64 v[140:141], v[4:5], 0, s[16:17]
	s_movk_i32 s16, 0x240
	s_addc_u32 s81, s81, 0
	v_or_b32_e32 v2, 0x1000, v0
	v_mul_u32_u24_e32 v7, 0x110, v212
	v_or_b32_e32 v110, 2, v106
	v_or_b32_e32 v112, 8, v106
	v_or_b32_e32 v114, 10, v106
	v_or_b32_e32 v116, 16, v106
	v_or_b32_e32 v118, 18, v106
	v_or_b32_e32 v120, 24, v106
	v_or_b32_e32 v122, 26, v106
	v_or_b32_e32 v124, 32, v106
	v_or_b32_e32 v126, 34, v106
	v_or_b32_e32 v128, 40, v106
	v_or_b32_e32 v129, 43, v106
	v_or_b32_e32 v130, 42, v106
	v_or_b32_e32 v131, 49, v106
	v_or_b32_e32 v132, 48, v106
	v_or_b32_e32 v133, 51, v106
	v_or_b32_e32 v134, 50, v106
	v_or_b32_e32 v135, 57, v106
	v_or_b32_e32 v136, 56, v106
	v_or_b32_e32 v137, 59, v106
	v_or_b32_e32 v138, 58, v106
	v_mad_u32_u24 v241, v1, s16, v6
	s_add_u32 s28, s0, 0x22c00000
	v_mbcnt_lo_u32_b32 v1, -1, 0
	s_mov_b32 s31, 0
	v_cmp_eq_u32_e64 s[4:5], 0, v176
	v_cmp_gt_u32_e64 s[6:7], 2, v176
	v_cmp_gt_u32_e64 s[8:9], 4, v176
	v_cmp_gt_u32_e64 s[10:11], 8, v176
	v_cmp_gt_u32_e64 s[12:13], 16, v176
	v_cmp_lt_u32_e64 s[14:15], 31, v176
	v_or_b32_e32 v107, 3, v106
	v_lshl_add_u32 v215, v110, 2, s93
	v_or_b32_e32 v111, 9, v106
	v_lshl_add_u32 v216, v112, 2, s93
	v_or_b32_e32 v113, 11, v106
	v_lshl_add_u32 v217, v114, 2, s93
	v_or_b32_e32 v115, 17, v106
	v_lshl_add_u32 v218, v116, 2, s93
	v_or_b32_e32 v117, 19, v106
	v_lshl_add_u32 v219, v118, 2, s93
	v_or_b32_e32 v119, 25, v106
	v_lshl_add_u32 v220, v120, 2, s93
	v_or_b32_e32 v121, 27, v106
	v_lshl_add_u32 v221, v122, 2, s93
	v_or_b32_e32 v123, 33, v106
	v_lshl_add_u32 v228, v124, 2, s93
	v_or_b32_e32 v125, 35, v106
	v_lshl_add_u32 v229, v126, 2, s93
	v_or_b32_e32 v127, 41, v106
	v_lshl_add_u32 v230, v128, 2, s93
	v_lshl_add_u32 v231, v130, 2, s93
	v_lshl_add_u32 v232, v129, 2, s93
	v_lshl_add_u32 v233, v132, 2, s93
	v_lshl_add_u32 v234, v131, 2, s93
	v_lshl_add_u32 v235, v134, 2, s93
	v_lshl_add_u32 v236, v133, 2, s93
	v_lshl_add_u32 v237, v136, 2, s93
	v_lshl_add_u32 v238, v135, 2, s93
	v_lshl_add_u32 v239, v138, 2, s93
	v_lshl_add_u32 v240, v137, 2, s93
	v_mad_u32_u24 v242, v124, s21, v6
	v_mad_u32_u24 v243, v128, s21, v6
	v_mad_u32_u24 v244, v132, s21, v6
	v_mad_u32_u24 v245, v136, s21, v6
	s_addc_u32 s29, s1, 0
	v_mbcnt_hi_u32_b32 v246, -1, v1
	s_mov_b32 s26, 0xffff0000
	v_lshlrev_b32_e32 v142, 1, v108
	v_lshlrev_b32_e32 v144, 1, v0
	v_lshlrev_b32_e32 v146, 1, v2
	v_lshlrev_b32_e32 v148, 2, v106
	v_lshlrev_b32_e32 v150, 2, v112
	v_lshlrev_b32_e32 v152, 2, v116
	v_lshlrev_b32_e32 v154, 2, v120
	v_lshlrev_b32_e32 v156, 2, v124
	v_lshlrev_b32_e32 v158, 2, v128
	v_lshlrev_b32_e32 v160, 2, v132
	v_lshlrev_b32_e32 v162, 2, v136
	v_add_u32_e32 v247, v213, v7
	s_mov_b32 s27, 0x5040100
	v_add_u32_e32 v248, v213, v3
	v_mov_b32_e32 v249, 0x358637bd
	v_mov_b32_e32 v250, 0x260
	s_mov_b32 s24, 0
	s_mov_b32 s25, 0
	s_branch .LBB0_619

; #define LAS __attribute__((address_space(3)))
; __global__ void __launch_bounds__(512, 2) fwd_kernel(Args a) {
;     ...
;             for (int k = 0; k < nk + (sj >= 0 ? 1 : 0); ++k) ssd_passC_unit(a, sl, k < nk ? u0 + k * 2 * G : NBATCH * NCHUNK * 2 + sj, sid, w4, lane, bcnt, btarget);
;         }
;         __syncthreads();
;         LAS unsigned char* wlds = lds + wave * (32 * S5_LD);
;         for (int it = gw; it < NBATCH * 32 * 8 + NBATCH * 32; it += NGW) {
.LBB0_853:
	v_readlane_b32 s96, v254, 59
	v_readlane_b32 s0, v254, 1
	s_cmpk_lt_u32 s0, 0x100
	s_cbranch_scc0 .LBB0_893

; #define LAS __attribute__((address_space(3)))
; __global__ void __launch_bounds__(512, 2) fwd_kernel(Args a) {
;     ...
;             const int sb = wave >> 2, sid = tid & 255, w4 = wave & 3;
;             LAS unsigned char* sl = lds + sb * SUB_LDS; LAS unsigned* bcnt = (LAS unsigned*)(sl + L_SSD_END);
;             if (sid == 0) *bcnt = 0u;
;             __syncthreads();
;             unsigned btarget = 0u;
;             const bool spread = (G == 256);
;             const int ulim = spread ? NBATCH * NCHUNK * 2 : NUNITS_BC * 2, u0 = bx * 2 + sb;
;             const int nk = u0 < ulim ? (ulim - u0 + 2 * G - 1) / (2 * G) : 0;
.Lp4_after_s5:
	v_readlane_b32 s0, v254, 1
	s_cmpk_lt_u32 s0, 0x100
	s_cbranch_scc1 .LBB0_893
	s_mov_b32 s70, s98
	s_mov_b32 s71, s99
	s_mov_b32 s72, s100
	s_mov_b32 s73, s101
	v_and_b32_e32 v139, 0xff, v177
	s_lshr_b32 s2, s0, 8
	s_mul_i32 s0, s2, 0x12c40
	s_add_i32 s16, s0, 0
	s_mov_b32 s69, 0
	s_add_i32 s19, s16, 0x12c00
	v_readlane_b32 s0, v254, 41
	v_readlane_b32 s1, v254, 42
	s_cmpk_eq_i32 s0, 0x100
	s_cselect_b64 s[0:1], -1, 0
	s_movk_i32 s3, 0x800
	s_and_b64 s[4:5], s[0:1], exec
	s_cselect_b32 s3, s3, 0x810
	s_lshl_b32 s4, s96, 1
	s_add_i32 s2, s2, s4
	s_mov_b32 s22, s2
	s_cmp_ge_i32 s2, s3
	s_cbranch_scc1 .Lp4r_614
	v_readlane_b32 s4, v254, 41
	s_lshl_b32 s2, s4, 1
	s_abs_i32 s4, s2
	v_cvt_f32_u32_e32 v0, s4
	v_readlane_b32 s5, v254, 42
	s_not_b32 s5, s22
	s_add_i32 s5, s2, s5
	v_rcp_iflag_f32_e32 v0, v0
	s_add_i32 s5, s5, s3
	s_sub_i32 s3, 0, s4
	s_xor_b32 s2, s5, s2
	v_mul_f32_e32 v0, 0x4f7ffffe, v0
	v_cvt_u32_f32_e32 v0, v0
	s_abs_i32 s5, s5
	s_ashr_i32 s2, s2, 31
	v_readfirstlane_b32 s6, v0
	s_mul_i32 s3, s3, s6
	s_mul_hi_u32 s3, s6, s3
	s_add_i32 s6, s6, s3
	s_mul_hi_u32 s3, s5, s6
	s_mul_i32 s6, s3, s4
	s_sub_i32 s5, s5, s6
	s_add_i32 s7, s3, 1
	s_sub_i32 s6, s5, s4
	s_cmp_ge_u32 s5, s4
	s_cselect_b32 s3, s7, s3
	s_cselect_b32 s5, s6, s5
	s_add_i32 s6, s3, 1
	s_cmp_ge_u32 s5, s4
	s_cselect_b32 s3, s6, s3
	s_xor_b32 s3, s3, s2
	s_sub_i32 s69, s3, s2

; __global__ void __launch_bounds__(512, 2) fwd_kernel(Args a) {
;     ...
;             const int sj = (spread && sb == 0 && (bx & 15) == 8) ? (bx >> 4) : -1;
;             if (sb) __builtin_amdgcn_s_sleep(100);
;             for (int k = 0; k < nk + (sj >= 0 ? 1 : 0); ++k) ssd_passC_unit(a, sl, k < nk ? u0 + k * 2 * G : NBATCH * NCHUNK * 2 + sj, sid, w4, lane, bcnt, btarget);
.Lp4r_616:
	s_and_b32 s4, s96, 15
	s_cmp_eq_u32 s4, 8
	s_cselect_b64 s[4:5], -1, 0
	s_and_b64 s[2:3], s[4:5], s[2:3]
	s_and_b64 s[0:1], s[2:3], s[0:1]
	s_ashr_i32 s2, s96, 4
	s_and_b64 s[0:1], s[0:1], exec
	s_cselect_b32 s75, s2, -1
	s_not_b32 s0, s75
	s_lshr_b32 s0, s0, 31
	s_add_i32 s74, s69, s0
	s_cmp_lt_i32 s74, 1
	v_cmp_gt_u32_e64 s[2:3], 32, v176
	s_cbranch_scc1 .LBB0_893
	s_branch .Lp4_ssd_setup

; #define LAS __attribute__((address_space(3)))
; __global__ void __launch_bounds__(512, 2) fwd_kernel(Args a) {
;     extern __shared__ __attribute__((aligned(16))) unsigned char lds_raw[];
;     LAS unsigned char* lds = (LAS unsigned char*)lds_raw;
;     const int tid = threadIdx.x, lane = tid & 63, wave = __builtin_amdgcn_readfirstlane(tid >> 6);
;     const int G = gridDim.x, bx = blockIdx.x;
;     const int gw = bx * 8 + wave, NGW = G * 8;
;     unsigned char* ws = a.ws;
	.amdhsa_kernel _Z10fwd_kernel4Args
		.amdhsa_group_segment_fixed_size 0
		.amdhsa_private_segment_fixed_size 0
		.amdhsa_kernarg_size 544
		.amdhsa_user_sgpr_count 2
		.amdhsa_user_sgpr_dispatch_ptr 0
		.amdhsa_user_sgpr_queue_ptr 0
		.amdhsa_user_sgpr_kernarg_segment_ptr 1
		.amdhsa_user_sgpr_dispatch_id 0
		.amdhsa_user_sgpr_kernarg_preload_length 0
		.amdhsa_user_sgpr_kernarg_preload_offset 0
		.amdhsa_user_sgpr_private_segment_size 0
		.amdhsa_uses_dynamic_stack 0
		.amdhsa_enable_private_segment 0
		.amdhsa_system_sgpr_workgroup_id_x 1
		.amdhsa_system_sgpr_workgroup_id_y 0
		.amdhsa_system_sgpr_workgroup_id_z 0
		.amdhsa_system_sgpr_workgroup_info 0
		.amdhsa_system_vgpr_workitem_id 2
		.amdhsa_next_free_vgpr 256
		.amdhsa_next_free_sgpr 102
		.amdhsa_accum_offset 256
		.amdhsa_reserve_vcc 1
		.amdhsa_float_round_mode_32 0
		.amdhsa_float_round_mode_16_64 0
		.amdhsa_float_denorm_mode_32 3
		.amdhsa_float_denorm_mode_16_64 3
		.amdhsa_dx10_clamp 1
		.amdhsa_ieee_mode 1
		.amdhsa_fp16_overflow 0
		.amdhsa_tg_split 0
		.amdhsa_exception_fp_ieee_invalid_op 0
		.amdhsa_exception_fp_denorm_src 0
		.amdhsa_exception_fp_ieee_div_zero 0
		.amdhsa_exception_fp_ieee_overflow 0
		.amdhsa_exception_fp_ieee_underflow 0
		.amdhsa_exception_fp_ieee_inexact 0
		.amdhsa_exception_int_div_zero 0
	.end_amdhsa_kernel

; __global__ void __launch_bounds__(512, 2) fwd_kernel(Args a) {
amdhsa.kernels:
  - .agpr_count:     0
    .args:
      - .offset:         0
        .size:           288
        .value_kind:     by_value
      - .offset:         288
        .size:           4
        .value_kind:     hidden_block_count_x
      - .offset:         292
        .size:           4
        .value_kind:     hidden_block_count_y
      - .offset:         296
        .size:           4
        .value_kind:     hidden_block_count_z
      - .offset:         300
        .size:           2
        .value_kind:     hidden_group_size_x
      - .offset:         302
        .size:           2
        .value_kind:     hidden_group_size_y
      - .offset:         304
        .size:           2
        .value_kind:     hidden_group_size_z
      - .offset:         306
        .size:           2
        .value_kind:     hidden_remainder_x
      - .offset:         308
        .size:           2
        .value_kind:     hidden_remainder_y
      - .offset:         310
        .size:           2
        .value_kind:     hidden_remainder_z
      - .offset:         328
        .size:           8
        .value_kind:     hidden_global_offset_x
      - .offset:         336
        .size:           8
        .value_kind:     hidden_global_offset_y
      - .offset:         344
        .size:           8
        .value_kind:     hidden_global_offset_z
      - .offset:         352
        .size:           2
        .value_kind:     hidden_grid_dims
      - .offset:         376
        .size:           8
        .value_kind:     hidden_multigrid_sync_arg
      - .offset:         408
        .size:           4
        .value_kind:     hidden_dynamic_lds_size
    .group_segment_fixed_size: 0
    .kernarg_segment_align: 8
    .kernarg_segment_size: 544
    .language:       OpenCL C
    .language_version:
      - 2
      - 0
    .max_flat_workgroup_size: 512
    .name:           _Z10fwd_kernel4Args
    .private_segment_fixed_size: 0
    .sgpr_count:     108
    .sgpr_spill_count: 71
    .symbol:         _Z10fwd_kernel4Args.kd
    .uniform_work_group_size: 1
    .uses_dynamic_stack: false
    .vgpr_count:     256
    .vgpr_spill_count: 0
    .wavefront_size: 64
